# v34 plus MMA segments bounded exactly by barriers: setprio moved across the barriers and the redundant lgkmcnt wait after the barrier removed
# speedup vs baseline: 1.0086x; 1.0086x over previous
.LBB0_246:
	s_add_i32 s76, s88, 2
	s_add_u32 s33, s0, 0xfff80080
	s_addc_u32 s48, s1, -1
	s_add_i32 m0, s35, 0xc000
	s_add_i32 s77, s35, 0xe000
	global_load_lds_dwordx4 v146, s[0:1]
	s_mov_b32 m0, s77
	s_cmp_eq_u32 vcc_hi, s88
	global_load_lds_dwordx4 v148, s[0:1]
	s_cselect_b32 s88, vcc_lo, s56
	s_cselect_b32 s91, s69, s48
	s_cselect_b32 s90, s75, s33
	s_cselect_b32 s89, s73, s57
	s_add_i32 s33, 0, 0x10000
	s_add_i32 s96, 0, 0x14000
	ds_read_b128 v[150:153], v246
	ds_read_b128 v[154:157], v246 offset:1024
	ds_read_b128 v[158:161], v246 offset:2048
	ds_read_b128 v[162:165], v246 offset:3072
	ds_read_b128 v[166:169], v247
	ds_read_b128 v[170:173], v247 offset:1024
	ds_read_b128 v[174:177], v247 offset:2048
	ds_read_b128 v[178:181], v247 offset:3072
	ds_read_b128 v[182:185], v141
	ds_read_b128 v[186:189], v141 offset:1024
	ds_read_b128 v[190:193], v141 offset:2048
	ds_read_b128 v[194:197], v141 offset:3072
	ds_read_b128 v[198:201], v141 offset:4096
	ds_read_b128 v[202:205], v141 offset:5120
	ds_read_b128 v[210:213], v141 offset:6144
	ds_read_b128 v[214:217], v141 offset:7168
	s_waitcnt vmcnt(8)
	s_waitcnt lgkmcnt(0)
	s_setprio 1
	s_barrier
	v_mfma_f32_16x16x32_bf16 v[128:131], v[150:153], v[182:185], v[128:131]
	v_mfma_f32_16x16x32_bf16 v[124:127], v[158:161], v[182:185], v[124:127]
	v_mfma_f32_16x16x32_bf16 v[116:119], v[150:153], v[190:193], v[116:119]
	v_mfma_f32_16x16x32_bf16 v[108:111], v[158:161], v[190:193], v[108:111]
	v_mfma_f32_16x16x32_bf16 v[100:103], v[150:153], v[198:201], v[100:103]
	v_mfma_f32_16x16x32_bf16 v[92:95], v[158:161], v[198:201], v[92:95]
	v_mfma_f32_16x16x32_bf16 v[84:87], v[150:153], v[210:213], v[84:87]
	v_mfma_f32_16x16x32_bf16 v[76:79], v[158:161], v[210:213], v[76:79]
	v_mfma_f32_16x16x32_bf16 v[128:131], v[154:157], v[186:189], v[128:131]
	v_mfma_f32_16x16x32_bf16 v[124:127], v[162:165], v[186:189], v[124:127]
	v_mfma_f32_16x16x32_bf16 v[116:119], v[154:157], v[194:197], v[116:119]
	v_mfma_f32_16x16x32_bf16 v[108:111], v[162:165], v[194:197], v[108:111]
	v_mfma_f32_16x16x32_bf16 v[100:103], v[154:157], v[202:205], v[100:103]
	v_mfma_f32_16x16x32_bf16 v[92:95], v[162:165], v[202:205], v[92:95]
	v_mfma_f32_16x16x32_bf16 v[84:87], v[154:157], v[214:217], v[84:87]
	v_mfma_f32_16x16x32_bf16 v[76:79], v[162:165], v[214:217], v[76:79]
	v_mfma_f32_16x16x32_bf16 v[120:123], v[166:169], v[182:185], v[120:123]
	v_mfma_f32_16x16x32_bf16 v[112:115], v[174:177], v[182:185], v[112:115]
	v_mfma_f32_16x16x32_bf16 v[104:107], v[166:169], v[190:193], v[104:107]
	v_mfma_f32_16x16x32_bf16 v[96:99], v[174:177], v[190:193], v[96:99]
	v_mfma_f32_16x16x32_bf16 v[88:91], v[166:169], v[198:201], v[88:91]
	v_mfma_f32_16x16x32_bf16 v[80:83], v[174:177], v[198:201], v[80:83]
	v_mfma_f32_16x16x32_bf16 v[72:75], v[166:169], v[210:213], v[72:75]
	v_mfma_f32_16x16x32_bf16 v[68:71], v[174:177], v[210:213], v[68:71]
	v_mfma_f32_16x16x32_bf16 v[120:123], v[170:173], v[186:189], v[120:123]
	v_mfma_f32_16x16x32_bf16 v[112:115], v[178:181], v[186:189], v[112:115]
	v_mfma_f32_16x16x32_bf16 v[104:107], v[170:173], v[194:197], v[104:107]
	v_mfma_f32_16x16x32_bf16 v[96:99], v[178:181], v[194:197], v[96:99]
	v_mfma_f32_16x16x32_bf16 v[88:91], v[170:173], v[202:205], v[88:91]
	v_mfma_f32_16x16x32_bf16 v[80:83], v[178:181], v[202:205], v[80:83]
	v_mfma_f32_16x16x32_bf16 v[72:75], v[170:173], v[214:217], v[72:75]
	v_mfma_f32_16x16x32_bf16 v[68:71], v[178:181], v[214:217], v[68:71]
	s_barrier
	s_setprio 0
	s_add_i32 s48, s33, s29
	s_mov_b32 m0, s48
	s_nop 0
	global_load_lds_dwordx4 v134, s[88:89]
	s_add_i32 m0, s48, 0x2000
	s_add_u32 s78, s88, 0x80000
	s_addc_u32 s79, s89, 0
	s_add_i32 s48, s96, s29
	global_load_lds_dwordx4 v138, s[88:89]
	s_mov_b32 m0, s48
	s_nop 0
	global_load_lds_dwordx4 v134, s[78:79]
	s_add_i32 m0, s48, 0x2000
	s_nop 0
	global_load_lds_dwordx4 v138, s[78:79]
	s_mov_b32 m0, s35
	s_nop 0
	global_load_lds_dwordx4 v132, s[90:91]
	s_mov_b32 m0, s60
	s_nop 0
	global_load_lds_dwordx4 v136, s[90:91]
	ds_read_b128 v[182:185], v141 offset:16384
	ds_read_b128 v[186:189], v141 offset:17408
	ds_read_b128 v[190:193], v141 offset:18432
	ds_read_b128 v[194:197], v141 offset:19456
	ds_read_b128 v[198:201], v141 offset:20480
	ds_read_b128 v[202:205], v141 offset:21504
	ds_read_b128 v[210:213], v141 offset:22528
	ds_read_b128 v[214:217], v141 offset:23552
	s_waitcnt vmcnt(8)
	s_waitcnt lgkmcnt(0)
	s_setprio 1
	s_barrier
	v_mfma_f32_16x16x32_bf16 v[64:67], v[150:153], v[182:185], v[64:67]
	v_mfma_f32_16x16x32_bf16 v[60:63], v[158:161], v[182:185], v[60:63]
	v_mfma_f32_16x16x32_bf16 v[52:55], v[150:153], v[190:193], v[52:55]
	v_mfma_f32_16x16x32_bf16 v[44:47], v[158:161], v[190:193], v[44:47]
	v_mfma_f32_16x16x32_bf16 v[36:39], v[150:153], v[198:201], v[36:39]
	v_mfma_f32_16x16x32_bf16 v[28:31], v[158:161], v[198:201], v[28:31]
	v_mfma_f32_16x16x32_bf16 v[20:23], v[150:153], v[210:213], v[20:23]
	v_mfma_f32_16x16x32_bf16 v[12:15], v[158:161], v[210:213], v[12:15]
	v_mfma_f32_16x16x32_bf16 v[64:67], v[154:157], v[186:189], v[64:67]
	v_mfma_f32_16x16x32_bf16 v[60:63], v[162:165], v[186:189], v[60:63]
	v_mfma_f32_16x16x32_bf16 v[52:55], v[154:157], v[194:197], v[52:55]
	v_mfma_f32_16x16x32_bf16 v[44:47], v[162:165], v[194:197], v[44:47]
	v_mfma_f32_16x16x32_bf16 v[36:39], v[154:157], v[202:205], v[36:39]
	v_mfma_f32_16x16x32_bf16 v[28:31], v[162:165], v[202:205], v[28:31]
	v_mfma_f32_16x16x32_bf16 v[20:23], v[154:157], v[214:217], v[20:23]
	v_mfma_f32_16x16x32_bf16 v[12:15], v[162:165], v[214:217], v[12:15]
	v_mfma_f32_16x16x32_bf16 v[56:59], v[166:169], v[182:185], v[56:59]
	v_mfma_f32_16x16x32_bf16 v[48:51], v[174:177], v[182:185], v[48:51]
	v_mfma_f32_16x16x32_bf16 v[40:43], v[166:169], v[190:193], v[40:43]
	v_mfma_f32_16x16x32_bf16 v[32:35], v[174:177], v[190:193], v[32:35]
	v_mfma_f32_16x16x32_bf16 v[24:27], v[166:169], v[198:201], v[24:27]
	v_mfma_f32_16x16x32_bf16 v[16:19], v[174:177], v[198:201], v[16:19]
	v_mfma_f32_16x16x32_bf16 v[8:11], v[166:169], v[210:213], v[8:11]
	v_mfma_f32_16x16x32_bf16 v[4:7], v[174:177], v[210:213], v[4:7]
	v_mfma_f32_16x16x32_bf16 v[56:59], v[170:173], v[186:189], v[56:59]
	v_mfma_f32_16x16x32_bf16 v[48:51], v[178:181], v[186:189], v[48:51]
	v_mfma_f32_16x16x32_bf16 v[40:43], v[170:173], v[194:197], v[40:43]
	v_mfma_f32_16x16x32_bf16 v[32:35], v[178:181], v[194:197], v[32:35]
	v_mfma_f32_16x16x32_bf16 v[24:27], v[170:173], v[202:205], v[24:27]
	v_mfma_f32_16x16x32_bf16 v[16:19], v[178:181], v[202:205], v[16:19]
	v_mfma_f32_16x16x32_bf16 v[8:11], v[170:173], v[214:217], v[8:11]
	v_mfma_f32_16x16x32_bf16 v[4:7], v[178:181], v[214:217], v[4:7]
	s_barrier
	s_setprio 0
	s_add_u32 s78, s90, 0x80000
	s_addc_u32 s79, s91, 0
	s_mov_b32 m0, s61
	s_nop 0
	global_load_lds_dwordx4 v132, s[78:79]
	s_mov_b32 m0, s62
	s_nop 0
	global_load_lds_dwordx4 v136, s[78:79]
	s_add_i32 s97, 0, 0x18000
	s_add_i32 s48, 0, 0x1c000
	ds_read_b128 v[150:153], v248
	ds_read_b128 v[154:157], v248 offset:1024
	ds_read_b128 v[158:161], v248 offset:2048
	ds_read_b128 v[162:165], v248 offset:3072
	ds_read_b128 v[166:169], v249
	ds_read_b128 v[170:173], v249 offset:1024
	ds_read_b128 v[174:177], v249 offset:2048
	ds_read_b128 v[178:181], v249 offset:3072
	ds_read_b128 v[182:185], v141 offset:32768
	ds_read_b128 v[186:189], v141 offset:33792
	ds_read_b128 v[190:193], v141 offset:34816
	ds_read_b128 v[194:197], v141 offset:35840
	ds_read_b128 v[198:201], v141 offset:36864
	ds_read_b128 v[202:205], v141 offset:37888
	ds_read_b128 v[210:213], v141 offset:38912
	ds_read_b128 v[214:217], v141 offset:39936
	s_waitcnt vmcnt(8)
	s_waitcnt lgkmcnt(0)
	s_setprio 1
	s_barrier
	v_mfma_f32_16x16x32_bf16 v[128:131], v[150:153], v[182:185], v[128:131]
	v_mfma_f32_16x16x32_bf16 v[124:127], v[158:161], v[182:185], v[124:127]
	v_mfma_f32_16x16x32_bf16 v[116:119], v[150:153], v[190:193], v[116:119]
	v_mfma_f32_16x16x32_bf16 v[108:111], v[158:161], v[190:193], v[108:111]
	v_mfma_f32_16x16x32_bf16 v[100:103], v[150:153], v[198:201], v[100:103]
	v_mfma_f32_16x16x32_bf16 v[92:95], v[158:161], v[198:201], v[92:95]
	v_mfma_f32_16x16x32_bf16 v[84:87], v[150:153], v[210:213], v[84:87]
	v_mfma_f32_16x16x32_bf16 v[76:79], v[158:161], v[210:213], v[76:79]
	v_mfma_f32_16x16x32_bf16 v[128:131], v[154:157], v[186:189], v[128:131]
	v_mfma_f32_16x16x32_bf16 v[124:127], v[162:165], v[186:189], v[124:127]
	v_mfma_f32_16x16x32_bf16 v[116:119], v[154:157], v[194:197], v[116:119]
	v_mfma_f32_16x16x32_bf16 v[108:111], v[162:165], v[194:197], v[108:111]
	v_mfma_f32_16x16x32_bf16 v[100:103], v[154:157], v[202:205], v[100:103]
	v_mfma_f32_16x16x32_bf16 v[92:95], v[162:165], v[202:205], v[92:95]
	v_mfma_f32_16x16x32_bf16 v[84:87], v[154:157], v[214:217], v[84:87]
	v_mfma_f32_16x16x32_bf16 v[76:79], v[162:165], v[214:217], v[76:79]
	v_mfma_f32_16x16x32_bf16 v[120:123], v[166:169], v[182:185], v[120:123]
	v_mfma_f32_16x16x32_bf16 v[112:115], v[174:177], v[182:185], v[112:115]
	v_mfma_f32_16x16x32_bf16 v[104:107], v[166:169], v[190:193], v[104:107]
	v_mfma_f32_16x16x32_bf16 v[96:99], v[174:177], v[190:193], v[96:99]
	v_mfma_f32_16x16x32_bf16 v[88:91], v[166:169], v[198:201], v[88:91]
	v_mfma_f32_16x16x32_bf16 v[80:83], v[174:177], v[198:201], v[80:83]
	v_mfma_f32_16x16x32_bf16 v[72:75], v[166:169], v[210:213], v[72:75]
	v_mfma_f32_16x16x32_bf16 v[68:71], v[174:177], v[210:213], v[68:71]
	v_mfma_f32_16x16x32_bf16 v[120:123], v[170:173], v[186:189], v[120:123]
	v_mfma_f32_16x16x32_bf16 v[112:115], v[178:181], v[186:189], v[112:115]
	v_mfma_f32_16x16x32_bf16 v[104:107], v[170:173], v[194:197], v[104:107]
	v_mfma_f32_16x16x32_bf16 v[96:99], v[178:181], v[194:197], v[96:99]
	v_mfma_f32_16x16x32_bf16 v[88:91], v[170:173], v[202:205], v[88:91]
	v_mfma_f32_16x16x32_bf16 v[80:83], v[178:181], v[202:205], v[80:83]
	v_mfma_f32_16x16x32_bf16 v[72:75], v[170:173], v[214:217], v[72:75]
	v_mfma_f32_16x16x32_bf16 v[68:71], v[178:181], v[214:217], v[68:71]
	s_barrier
	s_setprio 0
	s_add_i32 s77, s97, s29
	s_mov_b32 m0, s77
	s_nop 0
	s_add_u32 s98, s88, 0x80
	s_addc_u32 s99, s89, 0
	s_nop 0
	global_load_lds_dwordx4 v134, s[98:99]
	s_add_i32 m0, s77, 0x2000
	s_add_u32 s78, s88, 0x80080
	s_addc_u32 s79, s89, 0
	s_add_i32 s77, s48, s29
	global_load_lds_dwordx4 v138, s[98:99]
	s_mov_b32 m0, s77
	s_nop 0
	global_load_lds_dwordx4 v134, s[78:79]
	s_add_i32 m0, s77, 0x2000
	s_nop 0
	global_load_lds_dwordx4 v138, s[78:79]
	s_mov_b32 m0, s63
	s_nop 0
	s_add_u32 s98, s90, 0x80
	s_addc_u32 s99, s91, 0
	s_nop 0
	global_load_lds_dwordx4 v132, s[98:99]
	s_mov_b32 m0, s64
	s_nop 0
	global_load_lds_dwordx4 v136, s[98:99]
	ds_read_b128 v[182:185], v141 offset:49152
	ds_read_b128 v[186:189], v141 offset:50176
	ds_read_b128 v[190:193], v141 offset:51200
	ds_read_b128 v[194:197], v141 offset:52224
	ds_read_b128 v[198:201], v141 offset:53248
	ds_read_b128 v[202:205], v141 offset:54272
	ds_read_b128 v[210:213], v141 offset:55296
	ds_read_b128 v[214:217], v141 offset:56320
	s_waitcnt vmcnt(8)
	s_waitcnt lgkmcnt(0)
	s_setprio 1
	s_barrier
	v_mfma_f32_16x16x32_bf16 v[64:67], v[150:153], v[182:185], v[64:67]
	v_mfma_f32_16x16x32_bf16 v[60:63], v[158:161], v[182:185], v[60:63]
	v_mfma_f32_16x16x32_bf16 v[52:55], v[150:153], v[190:193], v[52:55]
	v_mfma_f32_16x16x32_bf16 v[44:47], v[158:161], v[190:193], v[44:47]
	v_mfma_f32_16x16x32_bf16 v[36:39], v[150:153], v[198:201], v[36:39]
	v_mfma_f32_16x16x32_bf16 v[28:31], v[158:161], v[198:201], v[28:31]
	v_mfma_f32_16x16x32_bf16 v[20:23], v[150:153], v[210:213], v[20:23]
	v_mfma_f32_16x16x32_bf16 v[12:15], v[158:161], v[210:213], v[12:15]
	v_mfma_f32_16x16x32_bf16 v[64:67], v[154:157], v[186:189], v[64:67]
	v_mfma_f32_16x16x32_bf16 v[60:63], v[162:165], v[186:189], v[60:63]
	v_mfma_f32_16x16x32_bf16 v[52:55], v[154:157], v[194:197], v[52:55]
	v_mfma_f32_16x16x32_bf16 v[44:47], v[162:165], v[194:197], v[44:47]
	v_mfma_f32_16x16x32_bf16 v[36:39], v[154:157], v[202:205], v[36:39]
	v_mfma_f32_16x16x32_bf16 v[28:31], v[162:165], v[202:205], v[28:31]
	v_mfma_f32_16x16x32_bf16 v[20:23], v[154:157], v[214:217], v[20:23]
	v_mfma_f32_16x16x32_bf16 v[12:15], v[162:165], v[214:217], v[12:15]
	v_mfma_f32_16x16x32_bf16 v[56:59], v[166:169], v[182:185], v[56:59]
	v_mfma_f32_16x16x32_bf16 v[48:51], v[174:177], v[182:185], v[48:51]
	v_mfma_f32_16x16x32_bf16 v[40:43], v[166:169], v[190:193], v[40:43]
	v_mfma_f32_16x16x32_bf16 v[32:35], v[174:177], v[190:193], v[32:35]
	v_mfma_f32_16x16x32_bf16 v[24:27], v[166:169], v[198:201], v[24:27]
	v_mfma_f32_16x16x32_bf16 v[16:19], v[174:177], v[198:201], v[16:19]
	v_mfma_f32_16x16x32_bf16 v[8:11], v[166:169], v[210:213], v[8:11]
	v_mfma_f32_16x16x32_bf16 v[4:7], v[174:177], v[210:213], v[4:7]
	v_mfma_f32_16x16x32_bf16 v[56:59], v[170:173], v[186:189], v[56:59]
	v_mfma_f32_16x16x32_bf16 v[48:51], v[178:181], v[186:189], v[48:51]
	v_mfma_f32_16x16x32_bf16 v[40:43], v[170:173], v[194:197], v[40:43]
	v_mfma_f32_16x16x32_bf16 v[32:35], v[178:181], v[194:197], v[32:35]
	v_mfma_f32_16x16x32_bf16 v[24:27], v[170:173], v[202:205], v[24:27]
	v_mfma_f32_16x16x32_bf16 v[16:19], v[178:181], v[202:205], v[16:19]
	v_mfma_f32_16x16x32_bf16 v[8:11], v[170:173], v[214:217], v[8:11]
	v_mfma_f32_16x16x32_bf16 v[4:7], v[178:181], v[214:217], v[4:7]
	s_barrier
	s_setprio 0
	s_add_u32 s0, s0, 0x100
	s_addc_u32 s1, s1, 0
	s_add_u32 s56, s56, 0x100
	s_addc_u32 s57, s57, 0
	s_cmp_ge_i32 s76, s55
	s_mov_b32 s88, s76
	s_cbranch_scc0 .LBB0_246
	s_and_b64 vcc, exec, s[58:59]
	s_cbranch_vccz .LBB0_249
	s_barrier

.LBB0_521:
	s_add_i32 s55, s54, 2
	s_add_u32 s56, s74, 0xfff80080
	s_addc_u32 s57, s75, -1
	s_add_i32 m0, s17, 0xc000
	s_add_i32 s76, s17, 0xe000
	global_load_lds_dwordx4 v138, s[74:75]
	s_mov_b32 m0, s76
	s_cmp_eq_u32 s9, s54
	global_load_lds_dwordx4 v140, s[74:75]
	s_cselect_b32 s87, s69, s57
	s_cselect_b32 s86, s68, s56
	s_cselect_b32 s85, s73, s35
	s_cselect_b32 s84, s72, s23
	ds_read_b128 v[146:149], v246
	ds_read_b128 v[150:153], v246 offset:1024
	ds_read_b128 v[154:157], v246 offset:2048
	ds_read_b128 v[158:161], v246 offset:3072
	ds_read_b128 v[162:165], v247
	ds_read_b128 v[166:169], v247 offset:1024
	ds_read_b128 v[170:173], v247 offset:2048
	ds_read_b128 v[174:177], v247 offset:3072
	ds_read_b128 v[178:181], v144
	ds_read_b128 v[182:185], v144 offset:1024
	ds_read_b128 v[186:189], v144 offset:2048
	ds_read_b128 v[190:193], v144 offset:3072
	ds_read_b128 v[194:197], v144 offset:4096
	ds_read_b128 v[198:201], v144 offset:5120
	ds_read_b128 v[202:205], v144 offset:6144
	ds_read_b128 v[210:213], v144 offset:7168
	s_waitcnt vmcnt(8)
	s_waitcnt lgkmcnt(0)
	s_setprio 1
	s_barrier
	v_mfma_f32_16x16x32_bf16 v[128:131], v[146:149], v[178:181], v[128:131]
	v_mfma_f32_16x16x32_bf16 v[124:127], v[154:157], v[178:181], v[124:127]
	v_mfma_f32_16x16x32_bf16 v[120:123], v[146:149], v[186:189], v[120:123]
	v_mfma_f32_16x16x32_bf16 v[116:119], v[154:157], v[186:189], v[116:119]
	v_mfma_f32_16x16x32_bf16 v[104:107], v[146:149], v[194:197], v[104:107]
	v_mfma_f32_16x16x32_bf16 v[100:103], v[154:157], v[194:197], v[100:103]
	v_mfma_f32_16x16x32_bf16 v[88:91], v[146:149], v[202:205], v[88:91]
	v_mfma_f32_16x16x32_bf16 v[84:87], v[154:157], v[202:205], v[84:87]
	v_mfma_f32_16x16x32_bf16 v[128:131], v[150:153], v[182:185], v[128:131]
	v_mfma_f32_16x16x32_bf16 v[124:127], v[158:161], v[182:185], v[124:127]
	v_mfma_f32_16x16x32_bf16 v[120:123], v[150:153], v[190:193], v[120:123]
	v_mfma_f32_16x16x32_bf16 v[116:119], v[158:161], v[190:193], v[116:119]
	v_mfma_f32_16x16x32_bf16 v[104:107], v[150:153], v[198:201], v[104:107]
	v_mfma_f32_16x16x32_bf16 v[100:103], v[158:161], v[198:201], v[100:103]
	v_mfma_f32_16x16x32_bf16 v[88:91], v[150:153], v[210:213], v[88:91]
	v_mfma_f32_16x16x32_bf16 v[84:87], v[158:161], v[210:213], v[84:87]
	v_mfma_f32_16x16x32_bf16 v[112:115], v[162:165], v[178:181], v[112:115]
	v_mfma_f32_16x16x32_bf16 v[108:111], v[170:173], v[178:181], v[108:111]
	v_mfma_f32_16x16x32_bf16 v[96:99], v[162:165], v[186:189], v[96:99]
	v_mfma_f32_16x16x32_bf16 v[92:95], v[170:173], v[186:189], v[92:95]
	v_mfma_f32_16x16x32_bf16 v[80:83], v[162:165], v[194:197], v[80:83]
	v_mfma_f32_16x16x32_bf16 v[76:79], v[170:173], v[194:197], v[76:79]
	v_mfma_f32_16x16x32_bf16 v[72:75], v[162:165], v[202:205], v[72:75]
	v_mfma_f32_16x16x32_bf16 v[68:71], v[170:173], v[202:205], v[68:71]
	v_mfma_f32_16x16x32_bf16 v[112:115], v[166:169], v[182:185], v[112:115]
	v_mfma_f32_16x16x32_bf16 v[108:111], v[174:177], v[182:185], v[108:111]
	v_mfma_f32_16x16x32_bf16 v[96:99], v[166:169], v[190:193], v[96:99]
	v_mfma_f32_16x16x32_bf16 v[92:95], v[174:177], v[190:193], v[92:95]
	v_mfma_f32_16x16x32_bf16 v[80:83], v[166:169], v[198:201], v[80:83]
	v_mfma_f32_16x16x32_bf16 v[76:79], v[174:177], v[198:201], v[76:79]
	v_mfma_f32_16x16x32_bf16 v[72:75], v[166:169], v[210:213], v[72:75]
	v_mfma_f32_16x16x32_bf16 v[68:71], v[174:177], v[210:213], v[68:71]
	s_barrier
	s_setprio 0
	s_add_i32 s54, s33, s16
	s_mov_b32 m0, s54
	s_nop 0
	global_load_lds_dwordx4 v2, s[84:85]
	s_add_i32 m0, s54, 0x2000
	s_add_u32 s56, s84, 0x80000
	s_addc_u32 s57, s85, 0
	s_add_i32 s54, s96, s16
	global_load_lds_dwordx4 v136, s[84:85]
	s_mov_b32 m0, s54
	s_nop 0
	global_load_lds_dwordx4 v2, s[56:57]
	s_add_i32 m0, s54, 0x2000
	s_nop 0
	global_load_lds_dwordx4 v136, s[56:57]
	s_mov_b32 m0, s17
	s_nop 0
	global_load_lds_dwordx4 v132, s[86:87]
	s_mov_b32 m0, s29
	s_nop 0
	global_load_lds_dwordx4 v134, s[86:87]
	ds_read_b128 v[178:181], v144 offset:16384
	ds_read_b128 v[182:185], v144 offset:17408
	ds_read_b128 v[186:189], v144 offset:18432
	ds_read_b128 v[190:193], v144 offset:19456
	ds_read_b128 v[194:197], v144 offset:20480
	ds_read_b128 v[198:201], v144 offset:21504
	ds_read_b128 v[202:205], v144 offset:22528
	ds_read_b128 v[210:213], v144 offset:23552
	s_waitcnt vmcnt(8)
	s_waitcnt lgkmcnt(0)
	s_setprio 1
	s_barrier
	v_mfma_f32_16x16x32_bf16 v[64:67], v[146:149], v[178:181], v[64:67]
	v_mfma_f32_16x16x32_bf16 v[60:63], v[154:157], v[178:181], v[60:63]
	v_mfma_f32_16x16x32_bf16 v[56:59], v[146:149], v[186:189], v[56:59]
	v_mfma_f32_16x16x32_bf16 v[52:55], v[154:157], v[186:189], v[52:55]
	v_mfma_f32_16x16x32_bf16 v[40:43], v[146:149], v[194:197], v[40:43]
	v_mfma_f32_16x16x32_bf16 v[36:39], v[154:157], v[194:197], v[36:39]
	v_mfma_f32_16x16x32_bf16 v[24:27], v[146:149], v[202:205], v[24:27]
	v_mfma_f32_16x16x32_bf16 v[20:23], v[154:157], v[202:205], v[20:23]
	v_mfma_f32_16x16x32_bf16 v[64:67], v[150:153], v[182:185], v[64:67]
	v_mfma_f32_16x16x32_bf16 v[60:63], v[158:161], v[182:185], v[60:63]
	v_mfma_f32_16x16x32_bf16 v[56:59], v[150:153], v[190:193], v[56:59]
	v_mfma_f32_16x16x32_bf16 v[52:55], v[158:161], v[190:193], v[52:55]
	v_mfma_f32_16x16x32_bf16 v[40:43], v[150:153], v[198:201], v[40:43]
	v_mfma_f32_16x16x32_bf16 v[36:39], v[158:161], v[198:201], v[36:39]
	v_mfma_f32_16x16x32_bf16 v[24:27], v[150:153], v[210:213], v[24:27]
	v_mfma_f32_16x16x32_bf16 v[20:23], v[158:161], v[210:213], v[20:23]
	v_mfma_f32_16x16x32_bf16 v[48:51], v[162:165], v[178:181], v[48:51]
	v_mfma_f32_16x16x32_bf16 v[44:47], v[170:173], v[178:181], v[44:47]
	v_mfma_f32_16x16x32_bf16 v[32:35], v[162:165], v[186:189], v[32:35]
	v_mfma_f32_16x16x32_bf16 v[28:31], v[170:173], v[186:189], v[28:31]
	v_mfma_f32_16x16x32_bf16 v[16:19], v[162:165], v[194:197], v[16:19]
	v_mfma_f32_16x16x32_bf16 v[12:15], v[170:173], v[194:197], v[12:15]
	v_mfma_f32_16x16x32_bf16 v[8:11], v[162:165], v[202:205], v[8:11]
	v_mfma_f32_16x16x32_bf16 v[4:7], v[170:173], v[202:205], v[4:7]
	v_mfma_f32_16x16x32_bf16 v[48:51], v[166:169], v[182:185], v[48:51]
	v_mfma_f32_16x16x32_bf16 v[44:47], v[174:177], v[182:185], v[44:47]
	v_mfma_f32_16x16x32_bf16 v[32:35], v[166:169], v[190:193], v[32:35]
	v_mfma_f32_16x16x32_bf16 v[28:31], v[174:177], v[190:193], v[28:31]
	v_mfma_f32_16x16x32_bf16 v[16:19], v[166:169], v[198:201], v[16:19]
	v_mfma_f32_16x16x32_bf16 v[12:15], v[174:177], v[198:201], v[12:15]
	v_mfma_f32_16x16x32_bf16 v[8:11], v[166:169], v[210:213], v[8:11]
	v_mfma_f32_16x16x32_bf16 v[4:7], v[174:177], v[210:213], v[4:7]
	s_barrier
	s_setprio 0
	s_add_u32 s56, s86, 0x80000
	s_addc_u32 s57, s87, 0
	s_mov_b32 m0, s60
	s_nop 0
	global_load_lds_dwordx4 v132, s[56:57]
	s_mov_b32 m0, s61
	s_nop 0
	global_load_lds_dwordx4 v134, s[56:57]
	ds_read_b128 v[146:149], v248
	ds_read_b128 v[150:153], v248 offset:1024
	ds_read_b128 v[154:157], v248 offset:2048
	ds_read_b128 v[158:161], v248 offset:3072
	ds_read_b128 v[162:165], v249
	ds_read_b128 v[166:169], v249 offset:1024
	ds_read_b128 v[170:173], v249 offset:2048
	ds_read_b128 v[174:177], v249 offset:3072
	ds_read_b128 v[178:181], v144 offset:32768
	ds_read_b128 v[182:185], v144 offset:33792
	ds_read_b128 v[186:189], v144 offset:34816
	ds_read_b128 v[190:193], v144 offset:35840
	ds_read_b128 v[194:197], v144 offset:36864
	ds_read_b128 v[198:201], v144 offset:37888
	ds_read_b128 v[202:205], v144 offset:38912
	ds_read_b128 v[210:213], v144 offset:39936
	s_waitcnt vmcnt(8)
	s_waitcnt lgkmcnt(0)
	s_setprio 1
	s_barrier
	v_mfma_f32_16x16x32_bf16 v[128:131], v[146:149], v[178:181], v[128:131]
	v_mfma_f32_16x16x32_bf16 v[124:127], v[154:157], v[178:181], v[124:127]
	v_mfma_f32_16x16x32_bf16 v[120:123], v[146:149], v[186:189], v[120:123]
	v_mfma_f32_16x16x32_bf16 v[116:119], v[154:157], v[186:189], v[116:119]
	v_mfma_f32_16x16x32_bf16 v[104:107], v[146:149], v[194:197], v[104:107]
	v_mfma_f32_16x16x32_bf16 v[100:103], v[154:157], v[194:197], v[100:103]
	v_mfma_f32_16x16x32_bf16 v[88:91], v[146:149], v[202:205], v[88:91]
	v_mfma_f32_16x16x32_bf16 v[84:87], v[154:157], v[202:205], v[84:87]
	v_mfma_f32_16x16x32_bf16 v[128:131], v[150:153], v[182:185], v[128:131]
	v_mfma_f32_16x16x32_bf16 v[124:127], v[158:161], v[182:185], v[124:127]
	v_mfma_f32_16x16x32_bf16 v[120:123], v[150:153], v[190:193], v[120:123]
	v_mfma_f32_16x16x32_bf16 v[116:119], v[158:161], v[190:193], v[116:119]
	v_mfma_f32_16x16x32_bf16 v[104:107], v[150:153], v[198:201], v[104:107]
	v_mfma_f32_16x16x32_bf16 v[100:103], v[158:161], v[198:201], v[100:103]
	v_mfma_f32_16x16x32_bf16 v[88:91], v[150:153], v[210:213], v[88:91]
	v_mfma_f32_16x16x32_bf16 v[84:87], v[158:161], v[210:213], v[84:87]
	v_mfma_f32_16x16x32_bf16 v[112:115], v[162:165], v[178:181], v[112:115]
	v_mfma_f32_16x16x32_bf16 v[108:111], v[170:173], v[178:181], v[108:111]
	v_mfma_f32_16x16x32_bf16 v[96:99], v[162:165], v[186:189], v[96:99]
	v_mfma_f32_16x16x32_bf16 v[92:95], v[170:173], v[186:189], v[92:95]
	v_mfma_f32_16x16x32_bf16 v[80:83], v[162:165], v[194:197], v[80:83]
	v_mfma_f32_16x16x32_bf16 v[76:79], v[170:173], v[194:197], v[76:79]
	v_mfma_f32_16x16x32_bf16 v[72:75], v[162:165], v[202:205], v[72:75]
	v_mfma_f32_16x16x32_bf16 v[68:71], v[170:173], v[202:205], v[68:71]
	v_mfma_f32_16x16x32_bf16 v[112:115], v[166:169], v[182:185], v[112:115]
	v_mfma_f32_16x16x32_bf16 v[108:111], v[174:177], v[182:185], v[108:111]
	v_mfma_f32_16x16x32_bf16 v[96:99], v[166:169], v[190:193], v[96:99]
	v_mfma_f32_16x16x32_bf16 v[92:95], v[174:177], v[190:193], v[92:95]
	v_mfma_f32_16x16x32_bf16 v[80:83], v[166:169], v[198:201], v[80:83]
	v_mfma_f32_16x16x32_bf16 v[76:79], v[174:177], v[198:201], v[76:79]
	v_mfma_f32_16x16x32_bf16 v[72:75], v[166:169], v[210:213], v[72:75]
	v_mfma_f32_16x16x32_bf16 v[68:71], v[174:177], v[210:213], v[68:71]
	s_barrier
	s_setprio 0
	s_add_i32 s54, s97, s16
	s_mov_b32 m0, s54
	s_nop 0
	s_add_u32 s98, s84, 0x80
	s_addc_u32 s99, s85, 0
	s_nop 0
	global_load_lds_dwordx4 v2, s[98:99]
	s_add_i32 m0, s54, 0x2000
	s_add_u32 s56, s84, 0x80080
	s_addc_u32 s57, s85, 0
	s_add_i32 s54, s48, s16
	global_load_lds_dwordx4 v136, s[98:99]
	s_mov_b32 m0, s54
	s_nop 0
	global_load_lds_dwordx4 v2, s[56:57]
	s_add_i32 m0, s54, 0x2000
	s_nop 0
	global_load_lds_dwordx4 v136, s[56:57]
	s_mov_b32 m0, s62
	s_nop 0
	s_add_u32 s98, s86, 0x80
	s_addc_u32 s99, s87, 0
	s_nop 0
	global_load_lds_dwordx4 v132, s[98:99]
	s_mov_b32 m0, s63
	s_nop 0
	global_load_lds_dwordx4 v134, s[98:99]
	ds_read_b128 v[178:181], v144 offset:49152
	ds_read_b128 v[182:185], v144 offset:50176
	ds_read_b128 v[186:189], v144 offset:51200
	ds_read_b128 v[190:193], v144 offset:52224
	ds_read_b128 v[194:197], v144 offset:53248
	ds_read_b128 v[198:201], v144 offset:54272
	ds_read_b128 v[202:205], v144 offset:55296
	ds_read_b128 v[210:213], v144 offset:56320
	s_waitcnt vmcnt(8)
	s_waitcnt lgkmcnt(0)
	s_setprio 1
	s_barrier
	v_mfma_f32_16x16x32_bf16 v[64:67], v[146:149], v[178:181], v[64:67]
	v_mfma_f32_16x16x32_bf16 v[60:63], v[154:157], v[178:181], v[60:63]
	v_mfma_f32_16x16x32_bf16 v[56:59], v[146:149], v[186:189], v[56:59]
	v_mfma_f32_16x16x32_bf16 v[52:55], v[154:157], v[186:189], v[52:55]
	v_mfma_f32_16x16x32_bf16 v[40:43], v[146:149], v[194:197], v[40:43]
	v_mfma_f32_16x16x32_bf16 v[36:39], v[154:157], v[194:197], v[36:39]
	v_mfma_f32_16x16x32_bf16 v[24:27], v[146:149], v[202:205], v[24:27]
	v_mfma_f32_16x16x32_bf16 v[20:23], v[154:157], v[202:205], v[20:23]
	v_mfma_f32_16x16x32_bf16 v[64:67], v[150:153], v[182:185], v[64:67]
	v_mfma_f32_16x16x32_bf16 v[60:63], v[158:161], v[182:185], v[60:63]
	v_mfma_f32_16x16x32_bf16 v[56:59], v[150:153], v[190:193], v[56:59]
	v_mfma_f32_16x16x32_bf16 v[52:55], v[158:161], v[190:193], v[52:55]
	v_mfma_f32_16x16x32_bf16 v[40:43], v[150:153], v[198:201], v[40:43]
	v_mfma_f32_16x16x32_bf16 v[36:39], v[158:161], v[198:201], v[36:39]
	v_mfma_f32_16x16x32_bf16 v[24:27], v[150:153], v[210:213], v[24:27]
	v_mfma_f32_16x16x32_bf16 v[20:23], v[158:161], v[210:213], v[20:23]
	v_mfma_f32_16x16x32_bf16 v[48:51], v[162:165], v[178:181], v[48:51]
	v_mfma_f32_16x16x32_bf16 v[44:47], v[170:173], v[178:181], v[44:47]
	v_mfma_f32_16x16x32_bf16 v[32:35], v[162:165], v[186:189], v[32:35]
	v_mfma_f32_16x16x32_bf16 v[28:31], v[170:173], v[186:189], v[28:31]
	v_mfma_f32_16x16x32_bf16 v[16:19], v[162:165], v[194:197], v[16:19]
	v_mfma_f32_16x16x32_bf16 v[12:15], v[170:173], v[194:197], v[12:15]
	v_mfma_f32_16x16x32_bf16 v[8:11], v[162:165], v[202:205], v[8:11]
	v_mfma_f32_16x16x32_bf16 v[4:7], v[170:173], v[202:205], v[4:7]
	v_mfma_f32_16x16x32_bf16 v[48:51], v[166:169], v[182:185], v[48:51]
	v_mfma_f32_16x16x32_bf16 v[44:47], v[174:177], v[182:185], v[44:47]
	v_mfma_f32_16x16x32_bf16 v[32:35], v[166:169], v[190:193], v[32:35]
	v_mfma_f32_16x16x32_bf16 v[28:31], v[174:177], v[190:193], v[28:31]
	v_mfma_f32_16x16x32_bf16 v[16:19], v[166:169], v[198:201], v[16:19]
	v_mfma_f32_16x16x32_bf16 v[12:15], v[174:177], v[198:201], v[12:15]
	v_mfma_f32_16x16x32_bf16 v[8:11], v[166:169], v[210:213], v[8:11]
	v_mfma_f32_16x16x32_bf16 v[4:7], v[174:177], v[210:213], v[4:7]
	s_barrier
	s_setprio 0
	s_add_u32 s74, s74, 0x100
	s_addc_u32 s75, s75, 0
	s_add_u32 s23, s23, 0x100
	s_addc_u32 s35, s35, 0
	s_cmp_ge_u32 s55, s64
	s_mov_b32 s54, s55
	s_cbranch_scc0 .LBB0_521
	s_and_b64 vcc, exec, s[58:59]
	s_cbranch_vccz .LBB0_524
	s_barrier

.LBB0_694:
	s_add_u32 s57, s88, 0xfff80080
	s_addc_u32 s73, s89, -1
	s_add_i32 m0, s60, 0xc000
	s_add_i32 s75, s60, 0xe000
	global_load_lds_dwordx4 v138, s[88:89]
	s_mov_b32 m0, s75
	s_cmp_eq_u32 s56, 28
	global_load_lds_dwordx4 v140, s[88:89]
	s_cselect_b32 vcc_hi, s16, s73
	s_cselect_b32 vcc_lo, s17, s57
	s_cselect_b32 s91, s50, s55
	s_cselect_b32 s90, s51, s54
	ds_read_b128 v[148:151], v246
	ds_read_b128 v[152:155], v246 offset:1024
	ds_read_b128 v[156:159], v246 offset:2048
	ds_read_b128 v[160:163], v246 offset:3072
	ds_read_b128 v[164:167], v247
	ds_read_b128 v[168:171], v247 offset:1024
	ds_read_b128 v[172:175], v247 offset:2048
	ds_read_b128 v[176:179], v247 offset:3072
	ds_read_b128 v[180:183], v146
	ds_read_b128 v[184:187], v146 offset:1024
	ds_read_b128 v[188:191], v146 offset:2048
	ds_read_b128 v[192:195], v146 offset:3072
	ds_read_b128 v[196:199], v146 offset:4096
	ds_read_b128 v[200:203], v146 offset:5120
	ds_read_b128 v[210:213], v146 offset:6144
	ds_read_b128 v[214:217], v146 offset:7168
	s_waitcnt vmcnt(8)
	s_waitcnt lgkmcnt(0)
	s_setprio 1
	s_barrier
	v_mfma_f32_16x16x32_bf16 v[128:131], v[148:151], v[180:183], v[128:131]
	v_mfma_f32_16x16x32_bf16 v[124:127], v[156:159], v[180:183], v[124:127]
	v_mfma_f32_16x16x32_bf16 v[112:115], v[148:151], v[188:191], v[112:115]
	v_mfma_f32_16x16x32_bf16 v[108:111], v[156:159], v[188:191], v[108:111]
	v_mfma_f32_16x16x32_bf16 v[96:99], v[148:151], v[196:199], v[96:99]
	v_mfma_f32_16x16x32_bf16 v[92:95], v[156:159], v[196:199], v[92:95]
	v_mfma_f32_16x16x32_bf16 v[80:83], v[148:151], v[210:213], v[80:83]
	v_mfma_f32_16x16x32_bf16 v[76:79], v[156:159], v[210:213], v[76:79]
	v_mfma_f32_16x16x32_bf16 v[128:131], v[152:155], v[184:187], v[128:131]
	v_mfma_f32_16x16x32_bf16 v[124:127], v[160:163], v[184:187], v[124:127]
	v_mfma_f32_16x16x32_bf16 v[112:115], v[152:155], v[192:195], v[112:115]
	v_mfma_f32_16x16x32_bf16 v[108:111], v[160:163], v[192:195], v[108:111]
	v_mfma_f32_16x16x32_bf16 v[96:99], v[152:155], v[200:203], v[96:99]
	v_mfma_f32_16x16x32_bf16 v[92:95], v[160:163], v[200:203], v[92:95]
	v_mfma_f32_16x16x32_bf16 v[80:83], v[152:155], v[214:217], v[80:83]
	v_mfma_f32_16x16x32_bf16 v[76:79], v[160:163], v[214:217], v[76:79]
	v_mfma_f32_16x16x32_bf16 v[120:123], v[164:167], v[180:183], v[120:123]
	v_mfma_f32_16x16x32_bf16 v[116:119], v[172:175], v[180:183], v[116:119]
	v_mfma_f32_16x16x32_bf16 v[104:107], v[164:167], v[188:191], v[104:107]
	v_mfma_f32_16x16x32_bf16 v[100:103], v[172:175], v[188:191], v[100:103]
	v_mfma_f32_16x16x32_bf16 v[88:91], v[164:167], v[196:199], v[88:91]
	v_mfma_f32_16x16x32_bf16 v[84:87], v[172:175], v[196:199], v[84:87]
	v_mfma_f32_16x16x32_bf16 v[72:75], v[164:167], v[210:213], v[72:75]
	v_mfma_f32_16x16x32_bf16 v[68:71], v[172:175], v[210:213], v[68:71]
	v_mfma_f32_16x16x32_bf16 v[120:123], v[168:171], v[184:187], v[120:123]
	v_mfma_f32_16x16x32_bf16 v[116:119], v[176:179], v[184:187], v[116:119]
	v_mfma_f32_16x16x32_bf16 v[104:107], v[168:171], v[192:195], v[104:107]
	v_mfma_f32_16x16x32_bf16 v[100:103], v[176:179], v[192:195], v[100:103]
	v_mfma_f32_16x16x32_bf16 v[88:91], v[168:171], v[200:203], v[88:91]
	v_mfma_f32_16x16x32_bf16 v[84:87], v[176:179], v[200:203], v[84:87]
	v_mfma_f32_16x16x32_bf16 v[72:75], v[168:171], v[214:217], v[72:75]
	v_mfma_f32_16x16x32_bf16 v[68:71], v[176:179], v[214:217], v[68:71]
	s_barrier
	s_setprio 0
	s_add_i32 s57, s33, s35
	s_mov_b32 m0, s57
	s_nop 0
	global_load_lds_dwordx4 v2, s[90:91]
	s_add_i32 m0, s57, 0x2000
	s_add_u32 s76, s90, 0x80000
	s_addc_u32 s77, s91, 0
	s_add_i32 s57, s96, s35
	global_load_lds_dwordx4 v132, s[90:91]
	s_mov_b32 m0, s57
	s_nop 0
	global_load_lds_dwordx4 v2, s[76:77]
	s_add_i32 m0, s57, 0x2000
	s_nop 0
	global_load_lds_dwordx4 v132, s[76:77]
	s_mov_b32 m0, s60
	s_nop 0
	global_load_lds_dwordx4 v136, vcc
	s_mov_b32 m0, s61
	s_nop 0
	global_load_lds_dwordx4 v134, vcc
	ds_read_b128 v[180:183], v146 offset:16384
	ds_read_b128 v[184:187], v146 offset:17408
	ds_read_b128 v[188:191], v146 offset:18432
	ds_read_b128 v[192:195], v146 offset:19456
	ds_read_b128 v[196:199], v146 offset:20480
	ds_read_b128 v[200:203], v146 offset:21504
	ds_read_b128 v[210:213], v146 offset:22528
	ds_read_b128 v[214:217], v146 offset:23552
	s_waitcnt vmcnt(8)
	s_waitcnt lgkmcnt(0)
	s_setprio 1
	s_barrier
	v_mfma_f32_16x16x32_bf16 v[64:67], v[148:151], v[180:183], v[64:67]
	v_mfma_f32_16x16x32_bf16 v[60:63], v[156:159], v[180:183], v[60:63]
	v_mfma_f32_16x16x32_bf16 v[48:51], v[148:151], v[188:191], v[48:51]
	v_mfma_f32_16x16x32_bf16 v[44:47], v[156:159], v[188:191], v[44:47]
	v_mfma_f32_16x16x32_bf16 v[32:35], v[148:151], v[196:199], v[32:35]
	v_mfma_f32_16x16x32_bf16 v[28:31], v[156:159], v[196:199], v[28:31]
	v_mfma_f32_16x16x32_bf16 v[16:19], v[148:151], v[210:213], v[16:19]
	v_mfma_f32_16x16x32_bf16 v[12:15], v[156:159], v[210:213], v[12:15]
	v_mfma_f32_16x16x32_bf16 v[64:67], v[152:155], v[184:187], v[64:67]
	v_mfma_f32_16x16x32_bf16 v[60:63], v[160:163], v[184:187], v[60:63]
	v_mfma_f32_16x16x32_bf16 v[48:51], v[152:155], v[192:195], v[48:51]
	v_mfma_f32_16x16x32_bf16 v[44:47], v[160:163], v[192:195], v[44:47]
	v_mfma_f32_16x16x32_bf16 v[32:35], v[152:155], v[200:203], v[32:35]
	v_mfma_f32_16x16x32_bf16 v[28:31], v[160:163], v[200:203], v[28:31]
	v_mfma_f32_16x16x32_bf16 v[16:19], v[152:155], v[214:217], v[16:19]
	v_mfma_f32_16x16x32_bf16 v[12:15], v[160:163], v[214:217], v[12:15]
	v_mfma_f32_16x16x32_bf16 v[56:59], v[164:167], v[180:183], v[56:59]
	v_mfma_f32_16x16x32_bf16 v[52:55], v[172:175], v[180:183], v[52:55]
	v_mfma_f32_16x16x32_bf16 v[40:43], v[164:167], v[188:191], v[40:43]
	v_mfma_f32_16x16x32_bf16 v[36:39], v[172:175], v[188:191], v[36:39]
	v_mfma_f32_16x16x32_bf16 v[24:27], v[164:167], v[196:199], v[24:27]
	v_mfma_f32_16x16x32_bf16 v[20:23], v[172:175], v[196:199], v[20:23]
	v_mfma_f32_16x16x32_bf16 v[8:11], v[164:167], v[210:213], v[8:11]
	v_mfma_f32_16x16x32_bf16 v[4:7], v[172:175], v[210:213], v[4:7]
	v_mfma_f32_16x16x32_bf16 v[56:59], v[168:171], v[184:187], v[56:59]
	v_mfma_f32_16x16x32_bf16 v[52:55], v[176:179], v[184:187], v[52:55]
	v_mfma_f32_16x16x32_bf16 v[40:43], v[168:171], v[192:195], v[40:43]
	v_mfma_f32_16x16x32_bf16 v[36:39], v[176:179], v[192:195], v[36:39]
	v_mfma_f32_16x16x32_bf16 v[24:27], v[168:171], v[200:203], v[24:27]
	v_mfma_f32_16x16x32_bf16 v[20:23], v[176:179], v[200:203], v[20:23]
	v_mfma_f32_16x16x32_bf16 v[8:11], v[168:171], v[214:217], v[8:11]
	v_mfma_f32_16x16x32_bf16 v[4:7], v[176:179], v[214:217], v[4:7]
	s_barrier
	s_setprio 0
	s_add_u32 s76, vcc_lo, 0x80000
	s_addc_u32 s77, vcc_hi, 0
	s_mov_b32 m0, s62
	s_nop 0
	global_load_lds_dwordx4 v136, s[76:77]
	s_mov_b32 m0, s63
	s_nop 0
	global_load_lds_dwordx4 v134, s[76:77]
	ds_read_b128 v[148:151], v248
	ds_read_b128 v[152:155], v248 offset:1024
	ds_read_b128 v[156:159], v248 offset:2048
	ds_read_b128 v[160:163], v248 offset:3072
	ds_read_b128 v[164:167], v249
	ds_read_b128 v[168:171], v249 offset:1024
	ds_read_b128 v[172:175], v249 offset:2048
	ds_read_b128 v[176:179], v249 offset:3072
	ds_read_b128 v[180:183], v146 offset:32768
	ds_read_b128 v[184:187], v146 offset:33792
	ds_read_b128 v[188:191], v146 offset:34816
	ds_read_b128 v[192:195], v146 offset:35840
	ds_read_b128 v[196:199], v146 offset:36864
	ds_read_b128 v[200:203], v146 offset:37888
	ds_read_b128 v[210:213], v146 offset:38912
	ds_read_b128 v[214:217], v146 offset:39936
	s_waitcnt vmcnt(8)
	s_waitcnt lgkmcnt(0)
	s_setprio 1
	s_barrier
	v_mfma_f32_16x16x32_bf16 v[128:131], v[148:151], v[180:183], v[128:131]
	v_mfma_f32_16x16x32_bf16 v[124:127], v[156:159], v[180:183], v[124:127]
	v_mfma_f32_16x16x32_bf16 v[112:115], v[148:151], v[188:191], v[112:115]
	v_mfma_f32_16x16x32_bf16 v[108:111], v[156:159], v[188:191], v[108:111]
	v_mfma_f32_16x16x32_bf16 v[96:99], v[148:151], v[196:199], v[96:99]
	v_mfma_f32_16x16x32_bf16 v[92:95], v[156:159], v[196:199], v[92:95]
	v_mfma_f32_16x16x32_bf16 v[80:83], v[148:151], v[210:213], v[80:83]
	v_mfma_f32_16x16x32_bf16 v[76:79], v[156:159], v[210:213], v[76:79]
	v_mfma_f32_16x16x32_bf16 v[128:131], v[152:155], v[184:187], v[128:131]
	v_mfma_f32_16x16x32_bf16 v[124:127], v[160:163], v[184:187], v[124:127]
	v_mfma_f32_16x16x32_bf16 v[112:115], v[152:155], v[192:195], v[112:115]
	v_mfma_f32_16x16x32_bf16 v[108:111], v[160:163], v[192:195], v[108:111]
	v_mfma_f32_16x16x32_bf16 v[96:99], v[152:155], v[200:203], v[96:99]
	v_mfma_f32_16x16x32_bf16 v[92:95], v[160:163], v[200:203], v[92:95]
	v_mfma_f32_16x16x32_bf16 v[80:83], v[152:155], v[214:217], v[80:83]
	v_mfma_f32_16x16x32_bf16 v[76:79], v[160:163], v[214:217], v[76:79]
	v_mfma_f32_16x16x32_bf16 v[120:123], v[164:167], v[180:183], v[120:123]
	v_mfma_f32_16x16x32_bf16 v[116:119], v[172:175], v[180:183], v[116:119]
	v_mfma_f32_16x16x32_bf16 v[104:107], v[164:167], v[188:191], v[104:107]
	v_mfma_f32_16x16x32_bf16 v[100:103], v[172:175], v[188:191], v[100:103]
	v_mfma_f32_16x16x32_bf16 v[88:91], v[164:167], v[196:199], v[88:91]
	v_mfma_f32_16x16x32_bf16 v[84:87], v[172:175], v[196:199], v[84:87]
	v_mfma_f32_16x16x32_bf16 v[72:75], v[164:167], v[210:213], v[72:75]
	v_mfma_f32_16x16x32_bf16 v[68:71], v[172:175], v[210:213], v[68:71]
	v_mfma_f32_16x16x32_bf16 v[120:123], v[168:171], v[184:187], v[120:123]
	v_mfma_f32_16x16x32_bf16 v[116:119], v[176:179], v[184:187], v[116:119]
	v_mfma_f32_16x16x32_bf16 v[104:107], v[168:171], v[192:195], v[104:107]
	v_mfma_f32_16x16x32_bf16 v[100:103], v[176:179], v[192:195], v[100:103]
	v_mfma_f32_16x16x32_bf16 v[88:91], v[168:171], v[200:203], v[88:91]
	v_mfma_f32_16x16x32_bf16 v[84:87], v[176:179], v[200:203], v[84:87]
	v_mfma_f32_16x16x32_bf16 v[72:75], v[168:171], v[214:217], v[72:75]
	v_mfma_f32_16x16x32_bf16 v[68:71], v[176:179], v[214:217], v[68:71]
	s_barrier
	s_setprio 0
	s_add_i32 s57, s97, s35
	s_mov_b32 m0, s57
	s_nop 0
	s_add_u32 s98, s90, 0x80
	s_addc_u32 s99, s91, 0
	s_nop 0
	global_load_lds_dwordx4 v2, s[98:99]
	s_add_i32 m0, s57, 0x2000
	s_add_u32 s76, s90, 0x80080
	s_addc_u32 s77, s91, 0
	s_add_i32 s57, s48, s35
	global_load_lds_dwordx4 v132, s[98:99]
	s_mov_b32 m0, s57
	s_nop 0
	global_load_lds_dwordx4 v2, s[76:77]
	s_add_i32 m0, s57, 0x2000
	s_nop 0
	global_load_lds_dwordx4 v132, s[76:77]
	s_mov_b32 m0, s64
	s_nop 0
	s_add_u32 s98, vcc_lo, 0x80
	s_addc_u32 s99, vcc_hi, 0
	s_nop 0
	global_load_lds_dwordx4 v136, s[98:99]
	s_mov_b32 m0, s58
	s_nop 0
	global_load_lds_dwordx4 v134, s[98:99]
	ds_read_b128 v[180:183], v146 offset:49152
	ds_read_b128 v[184:187], v146 offset:50176
	ds_read_b128 v[188:191], v146 offset:51200
	ds_read_b128 v[192:195], v146 offset:52224
	ds_read_b128 v[196:199], v146 offset:53248
	ds_read_b128 v[200:203], v146 offset:54272
	ds_read_b128 v[210:213], v146 offset:55296
	ds_read_b128 v[214:217], v146 offset:56320
	s_waitcnt vmcnt(8)
	s_waitcnt lgkmcnt(0)
	s_setprio 1
	s_barrier
	v_mfma_f32_16x16x32_bf16 v[64:67], v[148:151], v[180:183], v[64:67]
	v_mfma_f32_16x16x32_bf16 v[60:63], v[156:159], v[180:183], v[60:63]
	v_mfma_f32_16x16x32_bf16 v[48:51], v[148:151], v[188:191], v[48:51]
	v_mfma_f32_16x16x32_bf16 v[44:47], v[156:159], v[188:191], v[44:47]
	v_mfma_f32_16x16x32_bf16 v[32:35], v[148:151], v[196:199], v[32:35]
	v_mfma_f32_16x16x32_bf16 v[28:31], v[156:159], v[196:199], v[28:31]
	v_mfma_f32_16x16x32_bf16 v[16:19], v[148:151], v[210:213], v[16:19]
	v_mfma_f32_16x16x32_bf16 v[12:15], v[156:159], v[210:213], v[12:15]
	v_mfma_f32_16x16x32_bf16 v[64:67], v[152:155], v[184:187], v[64:67]
	v_mfma_f32_16x16x32_bf16 v[60:63], v[160:163], v[184:187], v[60:63]
	v_mfma_f32_16x16x32_bf16 v[48:51], v[152:155], v[192:195], v[48:51]
	v_mfma_f32_16x16x32_bf16 v[44:47], v[160:163], v[192:195], v[44:47]
	v_mfma_f32_16x16x32_bf16 v[32:35], v[152:155], v[200:203], v[32:35]
	v_mfma_f32_16x16x32_bf16 v[28:31], v[160:163], v[200:203], v[28:31]
	v_mfma_f32_16x16x32_bf16 v[16:19], v[152:155], v[214:217], v[16:19]
	v_mfma_f32_16x16x32_bf16 v[12:15], v[160:163], v[214:217], v[12:15]
	v_mfma_f32_16x16x32_bf16 v[56:59], v[164:167], v[180:183], v[56:59]
	v_mfma_f32_16x16x32_bf16 v[52:55], v[172:175], v[180:183], v[52:55]
	v_mfma_f32_16x16x32_bf16 v[40:43], v[164:167], v[188:191], v[40:43]
	v_mfma_f32_16x16x32_bf16 v[36:39], v[172:175], v[188:191], v[36:39]
	v_mfma_f32_16x16x32_bf16 v[24:27], v[164:167], v[196:199], v[24:27]
	v_mfma_f32_16x16x32_bf16 v[20:23], v[172:175], v[196:199], v[20:23]
	v_mfma_f32_16x16x32_bf16 v[8:11], v[164:167], v[210:213], v[8:11]
	v_mfma_f32_16x16x32_bf16 v[4:7], v[172:175], v[210:213], v[4:7]
	v_mfma_f32_16x16x32_bf16 v[56:59], v[168:171], v[184:187], v[56:59]
	v_mfma_f32_16x16x32_bf16 v[52:55], v[176:179], v[184:187], v[52:55]
	v_mfma_f32_16x16x32_bf16 v[40:43], v[168:171], v[192:195], v[40:43]
	v_mfma_f32_16x16x32_bf16 v[36:39], v[176:179], v[192:195], v[36:39]
	v_mfma_f32_16x16x32_bf16 v[24:27], v[168:171], v[200:203], v[24:27]
	v_mfma_f32_16x16x32_bf16 v[20:23], v[176:179], v[200:203], v[20:23]
	v_mfma_f32_16x16x32_bf16 v[8:11], v[168:171], v[214:217], v[8:11]
	v_mfma_f32_16x16x32_bf16 v[4:7], v[176:179], v[214:217], v[4:7]
	s_barrier
	s_setprio 0
	s_add_i32 s56, s56, 2
	s_add_u32 s88, s88, 0x100
	s_addc_u32 s89, s89, 0
	s_add_u32 s54, s54, 0x100
	s_addc_u32 s55, s55, 0
	s_cmp_gt_u32 s56, 29
	s_cbranch_scc0 .LBB0_694
	s_and_b64 vcc, exec, s[68:69]
	s_cbranch_vccz .LBB0_697
	s_barrier

.LBB0_763:
	s_add_i32 s56, s55, 2
	s_add_u32 s57, s84, 0xffe00080
	s_addc_u32 s62, s85, -1
	s_add_i32 m0, s16, 0xc000
	s_add_i32 s63, s16, 0xe000
	global_load_lds_dwordx4 v138, s[84:85]
	s_mov_b32 m0, s63
	s_cmp_eq_u32 s23, s55
	global_load_lds_dwordx4 v140, s[84:85]
	s_cselect_b32 s89, s73, s62
	s_cselect_b32 s88, s72, s57
	s_cselect_b32 s87, s75, s35
	s_cselect_b32 s86, s74, s29
	ds_read_b128 v[146:149], v246
	ds_read_b128 v[150:153], v246 offset:1024
	ds_read_b128 v[154:157], v246 offset:2048
	ds_read_b128 v[158:161], v246 offset:3072
	ds_read_b128 v[162:165], v247
	ds_read_b128 v[166:169], v247 offset:1024
	ds_read_b128 v[170:173], v247 offset:2048
	ds_read_b128 v[174:177], v247 offset:3072
	ds_read_b128 v[178:181], v144
	ds_read_b128 v[182:185], v144 offset:1024
	ds_read_b128 v[186:189], v144 offset:2048
	ds_read_b128 v[190:193], v144 offset:3072
	ds_read_b128 v[194:197], v144 offset:4096
	ds_read_b128 v[198:201], v144 offset:5120
	ds_read_b128 v[202:205], v144 offset:6144
	ds_read_b128 v[210:213], v144 offset:7168
	s_waitcnt vmcnt(8)
	s_waitcnt lgkmcnt(0)
	s_setprio 1
	s_barrier
	v_mfma_f32_16x16x32_bf16 v[128:131], v[146:149], v[178:181], v[128:131]
	v_mfma_f32_16x16x32_bf16 v[124:127], v[154:157], v[178:181], v[124:127]
	v_mfma_f32_16x16x32_bf16 v[120:123], v[146:149], v[186:189], v[120:123]
	v_mfma_f32_16x16x32_bf16 v[116:119], v[154:157], v[186:189], v[116:119]
	v_mfma_f32_16x16x32_bf16 v[104:107], v[146:149], v[194:197], v[104:107]
	v_mfma_f32_16x16x32_bf16 v[100:103], v[154:157], v[194:197], v[100:103]
	v_mfma_f32_16x16x32_bf16 v[88:91], v[146:149], v[202:205], v[88:91]
	v_mfma_f32_16x16x32_bf16 v[84:87], v[154:157], v[202:205], v[84:87]
	v_mfma_f32_16x16x32_bf16 v[128:131], v[150:153], v[182:185], v[128:131]
	v_mfma_f32_16x16x32_bf16 v[124:127], v[158:161], v[182:185], v[124:127]
	v_mfma_f32_16x16x32_bf16 v[120:123], v[150:153], v[190:193], v[120:123]
	v_mfma_f32_16x16x32_bf16 v[116:119], v[158:161], v[190:193], v[116:119]
	v_mfma_f32_16x16x32_bf16 v[104:107], v[150:153], v[198:201], v[104:107]
	v_mfma_f32_16x16x32_bf16 v[100:103], v[158:161], v[198:201], v[100:103]
	v_mfma_f32_16x16x32_bf16 v[88:91], v[150:153], v[210:213], v[88:91]
	v_mfma_f32_16x16x32_bf16 v[84:87], v[158:161], v[210:213], v[84:87]
	v_mfma_f32_16x16x32_bf16 v[112:115], v[162:165], v[178:181], v[112:115]
	v_mfma_f32_16x16x32_bf16 v[108:111], v[170:173], v[178:181], v[108:111]
	v_mfma_f32_16x16x32_bf16 v[96:99], v[162:165], v[186:189], v[96:99]
	v_mfma_f32_16x16x32_bf16 v[92:95], v[170:173], v[186:189], v[92:95]
	v_mfma_f32_16x16x32_bf16 v[80:83], v[162:165], v[194:197], v[80:83]
	v_mfma_f32_16x16x32_bf16 v[76:79], v[170:173], v[194:197], v[76:79]
	v_mfma_f32_16x16x32_bf16 v[72:75], v[162:165], v[202:205], v[72:75]
	v_mfma_f32_16x16x32_bf16 v[68:71], v[170:173], v[202:205], v[68:71]
	v_mfma_f32_16x16x32_bf16 v[112:115], v[166:169], v[182:185], v[112:115]
	v_mfma_f32_16x16x32_bf16 v[108:111], v[174:177], v[182:185], v[108:111]
	v_mfma_f32_16x16x32_bf16 v[96:99], v[166:169], v[190:193], v[96:99]
	v_mfma_f32_16x16x32_bf16 v[92:95], v[174:177], v[190:193], v[92:95]
	v_mfma_f32_16x16x32_bf16 v[80:83], v[166:169], v[198:201], v[80:83]
	v_mfma_f32_16x16x32_bf16 v[76:79], v[174:177], v[198:201], v[76:79]
	v_mfma_f32_16x16x32_bf16 v[72:75], v[166:169], v[210:213], v[72:75]
	v_mfma_f32_16x16x32_bf16 v[68:71], v[174:177], v[210:213], v[68:71]
	s_barrier
	s_setprio 0
	s_add_i32 s55, s33, s13
	s_mov_b32 m0, s55
	s_nop 0
	global_load_lds_dwordx4 v2, s[86:87]
	s_add_i32 m0, s55, 0x2000
	s_add_u32 s62, s86, 0x200000
	s_addc_u32 s63, s87, 0
	s_add_i32 s55, s96, s13
	global_load_lds_dwordx4 v136, s[86:87]
	s_mov_b32 m0, s55
	s_nop 0
	global_load_lds_dwordx4 v2, s[62:63]
	s_add_i32 m0, s55, 0x2000
	s_nop 0
	global_load_lds_dwordx4 v136, s[62:63]
	s_mov_b32 m0, s16
	s_nop 0
	global_load_lds_dwordx4 v132, s[88:89]
	s_mov_b32 m0, s17
	s_nop 0
	global_load_lds_dwordx4 v134, s[88:89]
	ds_read_b128 v[178:181], v144 offset:16384
	ds_read_b128 v[182:185], v144 offset:17408
	ds_read_b128 v[186:189], v144 offset:18432
	ds_read_b128 v[190:193], v144 offset:19456
	ds_read_b128 v[194:197], v144 offset:20480
	ds_read_b128 v[198:201], v144 offset:21504
	ds_read_b128 v[202:205], v144 offset:22528
	ds_read_b128 v[210:213], v144 offset:23552
	s_waitcnt vmcnt(8)
	s_waitcnt lgkmcnt(0)
	s_setprio 1
	s_barrier
	v_mfma_f32_16x16x32_bf16 v[64:67], v[146:149], v[178:181], v[64:67]
	v_mfma_f32_16x16x32_bf16 v[60:63], v[154:157], v[178:181], v[60:63]
	v_mfma_f32_16x16x32_bf16 v[56:59], v[146:149], v[186:189], v[56:59]
	v_mfma_f32_16x16x32_bf16 v[52:55], v[154:157], v[186:189], v[52:55]
	v_mfma_f32_16x16x32_bf16 v[40:43], v[146:149], v[194:197], v[40:43]
	v_mfma_f32_16x16x32_bf16 v[36:39], v[154:157], v[194:197], v[36:39]
	v_mfma_f32_16x16x32_bf16 v[24:27], v[146:149], v[202:205], v[24:27]
	v_mfma_f32_16x16x32_bf16 v[20:23], v[154:157], v[202:205], v[20:23]
	v_mfma_f32_16x16x32_bf16 v[64:67], v[150:153], v[182:185], v[64:67]
	v_mfma_f32_16x16x32_bf16 v[60:63], v[158:161], v[182:185], v[60:63]
	v_mfma_f32_16x16x32_bf16 v[56:59], v[150:153], v[190:193], v[56:59]
	v_mfma_f32_16x16x32_bf16 v[52:55], v[158:161], v[190:193], v[52:55]
	v_mfma_f32_16x16x32_bf16 v[40:43], v[150:153], v[198:201], v[40:43]
	v_mfma_f32_16x16x32_bf16 v[36:39], v[158:161], v[198:201], v[36:39]
	v_mfma_f32_16x16x32_bf16 v[24:27], v[150:153], v[210:213], v[24:27]
	v_mfma_f32_16x16x32_bf16 v[20:23], v[158:161], v[210:213], v[20:23]
	v_mfma_f32_16x16x32_bf16 v[48:51], v[162:165], v[178:181], v[48:51]
	v_mfma_f32_16x16x32_bf16 v[44:47], v[170:173], v[178:181], v[44:47]
	v_mfma_f32_16x16x32_bf16 v[32:35], v[162:165], v[186:189], v[32:35]
	v_mfma_f32_16x16x32_bf16 v[28:31], v[170:173], v[186:189], v[28:31]
	v_mfma_f32_16x16x32_bf16 v[16:19], v[162:165], v[194:197], v[16:19]
	v_mfma_f32_16x16x32_bf16 v[12:15], v[170:173], v[194:197], v[12:15]
	v_mfma_f32_16x16x32_bf16 v[8:11], v[162:165], v[202:205], v[8:11]
	v_mfma_f32_16x16x32_bf16 v[4:7], v[170:173], v[202:205], v[4:7]
	v_mfma_f32_16x16x32_bf16 v[48:51], v[166:169], v[182:185], v[48:51]
	v_mfma_f32_16x16x32_bf16 v[44:47], v[174:177], v[182:185], v[44:47]
	v_mfma_f32_16x16x32_bf16 v[32:35], v[166:169], v[190:193], v[32:35]
	v_mfma_f32_16x16x32_bf16 v[28:31], v[174:177], v[190:193], v[28:31]
	v_mfma_f32_16x16x32_bf16 v[16:19], v[166:169], v[198:201], v[16:19]
	v_mfma_f32_16x16x32_bf16 v[12:15], v[174:177], v[198:201], v[12:15]
	v_mfma_f32_16x16x32_bf16 v[8:11], v[166:169], v[210:213], v[8:11]
	v_mfma_f32_16x16x32_bf16 v[4:7], v[174:177], v[210:213], v[4:7]
	s_barrier
	s_setprio 0
	s_add_u32 s62, s88, 0x200000
	s_addc_u32 s63, s89, 0
	s_mov_b32 m0, s58
	s_nop 0
	global_load_lds_dwordx4 v132, s[62:63]
	s_mov_b32 m0, s59
	s_nop 0
	global_load_lds_dwordx4 v134, s[62:63]
	ds_read_b128 v[146:149], v248
	ds_read_b128 v[150:153], v248 offset:1024
	ds_read_b128 v[154:157], v248 offset:2048
	ds_read_b128 v[158:161], v248 offset:3072
	ds_read_b128 v[162:165], v249
	ds_read_b128 v[166:169], v249 offset:1024
	ds_read_b128 v[170:173], v249 offset:2048
	ds_read_b128 v[174:177], v249 offset:3072
	ds_read_b128 v[178:181], v144 offset:32768
	ds_read_b128 v[182:185], v144 offset:33792
	ds_read_b128 v[186:189], v144 offset:34816
	ds_read_b128 v[190:193], v144 offset:35840
	ds_read_b128 v[194:197], v144 offset:36864
	ds_read_b128 v[198:201], v144 offset:37888
	ds_read_b128 v[202:205], v144 offset:38912
	ds_read_b128 v[210:213], v144 offset:39936
	s_waitcnt vmcnt(8)
	s_waitcnt lgkmcnt(0)
	s_setprio 1
	s_barrier
	v_mfma_f32_16x16x32_bf16 v[128:131], v[146:149], v[178:181], v[128:131]
	v_mfma_f32_16x16x32_bf16 v[124:127], v[154:157], v[178:181], v[124:127]
	v_mfma_f32_16x16x32_bf16 v[120:123], v[146:149], v[186:189], v[120:123]
	v_mfma_f32_16x16x32_bf16 v[116:119], v[154:157], v[186:189], v[116:119]
	v_mfma_f32_16x16x32_bf16 v[104:107], v[146:149], v[194:197], v[104:107]
	v_mfma_f32_16x16x32_bf16 v[100:103], v[154:157], v[194:197], v[100:103]
	v_mfma_f32_16x16x32_bf16 v[88:91], v[146:149], v[202:205], v[88:91]
	v_mfma_f32_16x16x32_bf16 v[84:87], v[154:157], v[202:205], v[84:87]
	v_mfma_f32_16x16x32_bf16 v[128:131], v[150:153], v[182:185], v[128:131]
	v_mfma_f32_16x16x32_bf16 v[124:127], v[158:161], v[182:185], v[124:127]
	v_mfma_f32_16x16x32_bf16 v[120:123], v[150:153], v[190:193], v[120:123]
	v_mfma_f32_16x16x32_bf16 v[116:119], v[158:161], v[190:193], v[116:119]
	v_mfma_f32_16x16x32_bf16 v[104:107], v[150:153], v[198:201], v[104:107]
	v_mfma_f32_16x16x32_bf16 v[100:103], v[158:161], v[198:201], v[100:103]
	v_mfma_f32_16x16x32_bf16 v[88:91], v[150:153], v[210:213], v[88:91]
	v_mfma_f32_16x16x32_bf16 v[84:87], v[158:161], v[210:213], v[84:87]
	v_mfma_f32_16x16x32_bf16 v[112:115], v[162:165], v[178:181], v[112:115]
	v_mfma_f32_16x16x32_bf16 v[108:111], v[170:173], v[178:181], v[108:111]
	v_mfma_f32_16x16x32_bf16 v[96:99], v[162:165], v[186:189], v[96:99]
	v_mfma_f32_16x16x32_bf16 v[92:95], v[170:173], v[186:189], v[92:95]
	v_mfma_f32_16x16x32_bf16 v[80:83], v[162:165], v[194:197], v[80:83]
	v_mfma_f32_16x16x32_bf16 v[76:79], v[170:173], v[194:197], v[76:79]
	v_mfma_f32_16x16x32_bf16 v[72:75], v[162:165], v[202:205], v[72:75]
	v_mfma_f32_16x16x32_bf16 v[68:71], v[170:173], v[202:205], v[68:71]
	v_mfma_f32_16x16x32_bf16 v[112:115], v[166:169], v[182:185], v[112:115]
	v_mfma_f32_16x16x32_bf16 v[108:111], v[174:177], v[182:185], v[108:111]
	v_mfma_f32_16x16x32_bf16 v[96:99], v[166:169], v[190:193], v[96:99]
	v_mfma_f32_16x16x32_bf16 v[92:95], v[174:177], v[190:193], v[92:95]
	v_mfma_f32_16x16x32_bf16 v[80:83], v[166:169], v[198:201], v[80:83]
	v_mfma_f32_16x16x32_bf16 v[76:79], v[174:177], v[198:201], v[76:79]
	v_mfma_f32_16x16x32_bf16 v[72:75], v[166:169], v[210:213], v[72:75]
	v_mfma_f32_16x16x32_bf16 v[68:71], v[174:177], v[210:213], v[68:71]
	s_barrier
	s_setprio 0
	s_add_i32 s55, s97, s13
	s_mov_b32 m0, s55
	s_nop 0
	s_add_u32 s98, s86, 0x80
	s_addc_u32 s99, s87, 0
	s_nop 0
	global_load_lds_dwordx4 v2, s[98:99]
	s_add_i32 m0, s55, 0x2000
	s_add_u32 s62, s86, 0x200080
	s_addc_u32 s63, s87, 0
	s_add_i32 s55, s48, s13
	global_load_lds_dwordx4 v136, s[98:99]
	s_mov_b32 m0, s55
	s_nop 0
	global_load_lds_dwordx4 v2, s[62:63]
	s_add_i32 m0, s55, 0x2000
	s_nop 0
	global_load_lds_dwordx4 v136, s[62:63]
	s_mov_b32 m0, s60
	s_nop 0
	s_add_u32 s98, s88, 0x80
	s_addc_u32 s99, s89, 0
	s_nop 0
	global_load_lds_dwordx4 v132, s[98:99]
	s_mov_b32 m0, s61
	s_nop 0
	global_load_lds_dwordx4 v134, s[98:99]
	ds_read_b128 v[178:181], v144 offset:49152
	ds_read_b128 v[182:185], v144 offset:50176
	ds_read_b128 v[186:189], v144 offset:51200
	ds_read_b128 v[190:193], v144 offset:52224
	ds_read_b128 v[194:197], v144 offset:53248
	ds_read_b128 v[198:201], v144 offset:54272
	ds_read_b128 v[202:205], v144 offset:55296
	ds_read_b128 v[210:213], v144 offset:56320
	s_waitcnt vmcnt(8)
	s_waitcnt lgkmcnt(0)
	s_setprio 1
	s_barrier
	v_mfma_f32_16x16x32_bf16 v[64:67], v[146:149], v[178:181], v[64:67]
	v_mfma_f32_16x16x32_bf16 v[60:63], v[154:157], v[178:181], v[60:63]
	v_mfma_f32_16x16x32_bf16 v[56:59], v[146:149], v[186:189], v[56:59]
	v_mfma_f32_16x16x32_bf16 v[52:55], v[154:157], v[186:189], v[52:55]
	v_mfma_f32_16x16x32_bf16 v[40:43], v[146:149], v[194:197], v[40:43]
	v_mfma_f32_16x16x32_bf16 v[36:39], v[154:157], v[194:197], v[36:39]
	v_mfma_f32_16x16x32_bf16 v[24:27], v[146:149], v[202:205], v[24:27]
	v_mfma_f32_16x16x32_bf16 v[20:23], v[154:157], v[202:205], v[20:23]
	v_mfma_f32_16x16x32_bf16 v[64:67], v[150:153], v[182:185], v[64:67]
	v_mfma_f32_16x16x32_bf16 v[60:63], v[158:161], v[182:185], v[60:63]
	v_mfma_f32_16x16x32_bf16 v[56:59], v[150:153], v[190:193], v[56:59]
	v_mfma_f32_16x16x32_bf16 v[52:55], v[158:161], v[190:193], v[52:55]
	v_mfma_f32_16x16x32_bf16 v[40:43], v[150:153], v[198:201], v[40:43]
	v_mfma_f32_16x16x32_bf16 v[36:39], v[158:161], v[198:201], v[36:39]
	v_mfma_f32_16x16x32_bf16 v[24:27], v[150:153], v[210:213], v[24:27]
	v_mfma_f32_16x16x32_bf16 v[20:23], v[158:161], v[210:213], v[20:23]
	v_mfma_f32_16x16x32_bf16 v[48:51], v[162:165], v[178:181], v[48:51]
	v_mfma_f32_16x16x32_bf16 v[44:47], v[170:173], v[178:181], v[44:47]
	v_mfma_f32_16x16x32_bf16 v[32:35], v[162:165], v[186:189], v[32:35]
	v_mfma_f32_16x16x32_bf16 v[28:31], v[170:173], v[186:189], v[28:31]
	v_mfma_f32_16x16x32_bf16 v[16:19], v[162:165], v[194:197], v[16:19]
	v_mfma_f32_16x16x32_bf16 v[12:15], v[170:173], v[194:197], v[12:15]
	v_mfma_f32_16x16x32_bf16 v[8:11], v[162:165], v[202:205], v[8:11]
	v_mfma_f32_16x16x32_bf16 v[4:7], v[170:173], v[202:205], v[4:7]
	v_mfma_f32_16x16x32_bf16 v[48:51], v[166:169], v[182:185], v[48:51]
	v_mfma_f32_16x16x32_bf16 v[44:47], v[174:177], v[182:185], v[44:47]
	v_mfma_f32_16x16x32_bf16 v[32:35], v[166:169], v[190:193], v[32:35]
	v_mfma_f32_16x16x32_bf16 v[28:31], v[174:177], v[190:193], v[28:31]
	v_mfma_f32_16x16x32_bf16 v[16:19], v[166:169], v[198:201], v[16:19]
	v_mfma_f32_16x16x32_bf16 v[12:15], v[174:177], v[198:201], v[12:15]
	v_mfma_f32_16x16x32_bf16 v[8:11], v[166:169], v[210:213], v[8:11]
	v_mfma_f32_16x16x32_bf16 v[4:7], v[174:177], v[210:213], v[4:7]
	s_barrier
	s_setprio 0
	s_add_u32 s84, s84, 0x100
	s_addc_u32 s85, s85, 0
	s_add_u32 s29, s29, 0x100
	s_addc_u32 s35, s35, 0
	s_cmp_ge_u32 s56, s51
	s_mov_b32 s55, s56
	s_cbranch_scc0 .LBB0_763
	s_and_b64 vcc, exec, s[68:69]
	s_cbranch_vccz .LBB0_766
	s_barrier
